# baseline (speedup 1.0000x reference)
; DI void attn_item(const Params& p, unsigned char* lds, int b, int hd, int qb, float lam) {
;     ...
;     if (sub == 0) {
;         float ss = 0.f;
; #pragma unroll
;         for (int d = 0; d < 4; ++d) {
; #pragma unroll
;             for (int g = 0; g < 4; ++g) {
;                 const f32x4 t = *(const f32x4*)(ex + (rt * 32 + l31) * 132 + d * 32 + 8 * g + 4 * h);
;                 const float o0 = O[d][4 * g] * linv - lam * t.x, o1 = O[d][4 * g + 1] * linv - lam * t.y;
;                 const float o2 = O[d][4 * g + 2] * linv - lam * t.z, o3 = O[d][4 * g + 3] * linv - lam * t.w;
;                 O[d][4 * g] = o0; O[d][4 * g + 1] = o1; O[d][4 * g + 2] = o2; O[d][4 * g + 3] = o3;
;                 ss += (o0 * o0 + o1 * o1) + (o2 * o2 + o3 * o3);
;             }
;             __builtin_amdgcn_sched_barrier(0);
;         }
.LBB0_1828:
	s_or_b64 exec, exec, s[6:7]
	s_waitcnt lgkmcnt(0)
	s_barrier
	s_and_saveexec_b64 s[6:7], s[4:5]
	s_cbranch_execz .LBB0_1830
	v_add3_u32 v1, 0, v1, v98
	ds_read_b128 v[100:103], v1 offset:32
	ds_read_b128 v[66:69], v1
	v_mov_b32_e32 v82, v54
	v_mov_b32_e32 v104, v58
	v_mov_b32_e32 v58, v60
	s_waitcnt lgkmcnt(1)
	v_mov_b32_e32 v83, v100
	v_mov_b32_e32 v100, v55
	v_pk_mul_f32 v[54:55], v[134:135], v[102:103]
	v_pk_mul_f32 v[180:181], v[82:83], v[132:133]
	v_pk_fma_f32 v[82:83], v[56:57], v[132:133], v[54:55] op_sel_hi:[1,0,1] neg_lo:[0,0,1] neg_hi:[0,0,1]
	v_pk_mul_f32 v[184:185], v[100:101], v[132:133]
	ds_read_b128 v[100:103], v1 offset:64
	v_mul_f32_e32 v54, v83, v83
	v_pk_fma_f32 v[182:183], v[82:83], v[82:83], v[54:55] op_sel_hi:[1,1,0]
	ds_read_b128 v[54:57], v1 offset:96
	s_waitcnt lgkmcnt(1)
	v_mov_b32_e32 v105, v100
	v_mov_b32_e32 v100, v59
	v_mov_b32_e32 v59, v102
	v_pk_mul_f32 v[176:177], v[58:59], v[132:133]
	v_mov_b32_e32 v102, v61
	v_mov_b32_e32 v58, v64
	s_waitcnt lgkmcnt(0)
	v_mov_b32_e32 v59, v56
	v_mov_b32_e32 v56, v65
	v_pk_mul_f32 v[174:175], v[104:105], v[132:133]
	v_pk_mul_f32 v[170:171], v[100:101], v[132:133]
	v_pk_mul_f32 v[178:179], v[102:103], v[132:133]
	v_pk_mul_f32 v[168:169], v[58:59], v[132:133]
	v_pk_mul_f32 v[172:173], v[56:57], v[132:133]
	ds_read_b128 v[56:59], v1 offset:128
	ds_read_b128 v[100:103], v1 offset:160
	v_mov_b32_e32 v60, v34
	v_mov_b32_e32 v61, v36
	v_mov_b32_e32 v36, v35
	s_waitcnt lgkmcnt(1)
	v_mov_b32_e32 v65, v58
	v_mov_b32_e32 v58, v57
	v_mov_b32_e32 v64, v56
	v_pk_mul_f32 v[34:35], v[134:135], v[58:59]
	v_pk_mul_f32 v[64:65], v[134:135], v[64:65]
	v_pk_fma_f32 v[56:57], v[36:37], v[132:133], v[34:35] op_sel_hi:[1,0,1] neg_lo:[0,0,1] neg_hi:[0,0,1]
	v_pk_fma_f32 v[158:159], v[60:61], v[132:133], v[64:65] op_sel_hi:[1,0,1] neg_lo:[0,0,1] neg_hi:[0,0,1]
	v_pk_mul_f32 v[34:35], v[56:57], v[56:57]
	ds_read_b128 v[58:61], v1 offset:192
	v_pk_fma_f32 v[34:35], v[158:159], v[158:159], v[34:35]
	s_nop 0
	v_pk_add_f32 v[166:167], v[34:35], v[34:35] op_sel:[0,1] op_sel_hi:[1,0]
	v_mov_b32_e32 v34, v38
	s_waitcnt lgkmcnt(1)
	v_mov_b32_e32 v35, v100
	v_pk_mul_f32 v[160:161], v[34:35], v[132:133]
	v_pk_mul_f32 v[34:35], v[134:135], v[102:103]
	v_mov_b32_e32 v100, v39
	v_pk_fma_f32 v[38:39], v[40:41], v[132:133], v[34:35] op_sel_hi:[1,0,1] neg_lo:[0,0,1] neg_hi:[0,0,1]
	v_mov_b32_e32 v40, v42
	v_mul_f32_e32 v34, v39, v39
	v_pk_fma_f32 v[162:163], v[38:39], v[38:39], v[34:35] op_sel_hi:[1,1,0]
	ds_read_b128 v[34:37], v1 offset:224
	s_waitcnt lgkmcnt(1)
	v_mov_b32_e32 v41, v58
	v_pk_mul_f32 v[152:153], v[40:41], v[132:133]
	v_mov_b32_e32 v40, v44
	v_mov_b32_e32 v41, v60
	v_mov_b32_e32 v58, v43
	v_pk_mul_f32 v[154:155], v[40:41], v[132:133]
	v_mov_b32_e32 v60, v45
	v_mov_b32_e32 v40, v46
	s_waitcnt lgkmcnt(0)
	v_mov_b32_e32 v41, v34
	v_mul_f32_e32 v34, v34, v133
	v_mov_b32_e32 v42, v48
	v_mov_b32_e32 v43, v36
	v_mov_b32_e32 v36, v49
	v_pk_mul_f32 v[164:165], v[100:101], v[132:133]
	v_pk_mul_f32 v[144:145], v[58:59], v[132:133]
	v_pk_mul_f32 v[156:157], v[60:61], v[132:133]
	v_pk_fma_f32 v[40:41], v[40:41], v[132:133], v[34:35] op_sel_hi:[1,1,0] neg_lo:[0,0,1] neg_hi:[0,0,1]
	v_pk_mul_f32 v[148:149], v[42:43], v[132:133]
	v_pk_mul_f32 v[150:151], v[36:37], v[132:133]
	ds_read_b128 v[42:45], v1 offset:256
	ds_read_b128 v[58:61], v1 offset:288
	v_mov_b32_e32 v36, v18
	v_mov_b32_e32 v37, v20
	v_mov_b32_e32 v20, v19
	s_waitcnt lgkmcnt(1)
	v_mov_b32_e32 v48, v42
	v_mov_b32_e32 v49, v44
	v_mov_b32_e32 v44, v43
	v_pk_mul_f32 v[48:49], v[134:135], v[48:49]
	v_pk_mul_f32 v[18:19], v[134:135], v[44:45]
	v_pk_fma_f32 v[128:129], v[36:37], v[132:133], v[48:49] op_sel_hi:[1,0,1] neg_lo:[0,0,1] neg_hi:[0,0,1]
	v_pk_fma_f32 v[36:37], v[20:21], v[132:133], v[18:19] op_sel_hi:[1,0,1] neg_lo:[0,0,1] neg_hi:[0,0,1]
	ds_read_b128 v[42:45], v1 offset:320
	v_pk_mul_f32 v[18:19], v[36:37], v[36:37]
	s_nop 0
	v_pk_fma_f32 v[18:19], v[128:129], v[128:129], v[18:19]
	s_nop 0
	v_pk_add_f32 v[146:147], v[18:19], v[18:19] op_sel:[0,1] op_sel_hi:[1,0]
	v_mov_b32_e32 v18, v22
	s_waitcnt lgkmcnt(1)
	v_mov_b32_e32 v19, v58
	v_pk_mul_f32 v[138:139], v[18:19], v[132:133]
	v_pk_mul_f32 v[18:19], v[134:135], v[60:61]
	v_mov_b32_e32 v58, v23
	v_pk_fma_f32 v[22:23], v[24:25], v[132:133], v[18:19] op_sel_hi:[1,0,1] neg_lo:[0,0,1] neg_hi:[0,0,1]
	v_mov_b32_e32 v24, v26
	v_mul_f32_e32 v18, v23, v23
	v_pk_fma_f32 v[140:141], v[22:23], v[22:23], v[18:19] op_sel_hi:[1,1,0]
	ds_read_b128 v[18:21], v1 offset:352
	s_waitcnt lgkmcnt(1)
	v_mov_b32_e32 v25, v42
	v_pk_mul_f32 v[120:121], v[24:25], v[132:133]
	v_mov_b32_e32 v24, v28
	v_mov_b32_e32 v25, v44
	v_mov_b32_e32 v42, v27
	v_pk_mul_f32 v[122:123], v[24:25], v[132:133]
	v_mov_b32_e32 v44, v29
	v_mov_b32_e32 v24, v30
	s_waitcnt lgkmcnt(0)
	v_mov_b32_e32 v25, v18
	v_mul_f32_e32 v18, v18, v133
	v_mov_b32_e32 v26, v32
	v_mov_b32_e32 v27, v20
	v_mov_b32_e32 v20, v33
	v_pk_mul_f32 v[142:143], v[58:59], v[132:133]
	v_pk_mul_f32 v[112:113], v[42:43], v[132:133]
	v_pk_mul_f32 v[124:125], v[44:45], v[132:133]
	v_pk_fma_f32 v[24:25], v[24:25], v[132:133], v[18:19] op_sel_hi:[1,1,0] neg_lo:[0,0,1] neg_hi:[0,0,1]
	v_pk_mul_f32 v[116:117], v[26:27], v[132:133]
	v_pk_mul_f32 v[118:119], v[20:21], v[132:133]
	ds_read_b128 v[26:29], v1 offset:384
	ds_read_b128 v[42:45], v1 offset:416
	v_mov_b32_e32 v20, v2
	v_mov_b32_e32 v21, v4
	v_mov_b32_e32 v4, v3
	s_waitcnt lgkmcnt(1)
; DI unsigned pk2(float a, float b) { f32x2 v = {a, b}; return __builtin_bit_cast(unsigned, __builtin_convertvector(v, bfv2)); }
; DI float bflo(unsigned u) { return __uint_as_float(u << 16); }
; DI float bfhi(unsigned u) { return __uint_as_float(u & 0xffff0000u); }
; DI float xor32_sum(float x) { auto r = __builtin_amdgcn_permlane32_swap(__float_as_uint(x), __float_as_uint(x), false, false); return __uint_as_float(r[0]) + __uint_as_float(r[1]); }
; DI float siluf_(float z) { return z * __builtin_amdgcn_rcpf(1.f + __expf(-z)); }
; DI void attn_item(const Params& p, unsigned char* lds, int b, int hd, int qb, float lam) {
;     ...
;     if (sub == 0) {
;         float ss = 0.f;
; #pragma unroll
;         for (int d = 0; d < 4; ++d) {
; #pragma unroll
;             for (int g = 0; g < 4; ++g) {
;                 const f32x4 t = *(const f32x4*)(ex + (rt * 32 + l31) * 132 + d * 32 + 8 * g + 4 * h);
;                 const float o0 = O[d][4 * g] * linv - lam * t.x, o1 = O[d][4 * g + 1] * linv - lam * t.y;
;                 const float o2 = O[d][4 * g + 2] * linv - lam * t.z, o3 = O[d][4 * g + 3] * linv - lam * t.w;
;                 O[d][4 * g] = o0; O[d][4 * g + 1] = o1; O[d][4 * g + 2] = o2; O[d][4 * g + 3] = o3;
;                 ss += (o0 * o0 + o1 * o1) + (o2 * o2 + o3 * o3);
;             }
;             __builtin_amdgcn_sched_barrier(0);
;         }
;         ss = xor32_sum(ss);
;         const float rstd = 1.0f / sqrtf(ss * (1.0f / 128.0f) + EPS);
; #pragma unroll
;         for (int d = 0; d < 4; ++d)
; #pragma unroll
;             for (int g = 0; g < 4; ++g) {
;                 bf16_t* zp = az + grow * 1024 + hd * 128 + d * 32 + 8 * g + 4 * h;
;                 const u32x2 z2 = zz[d][g];
;                 u32x2 o;
;                 o.x = pk2(O[d][4 * g] * rstd * siluf_(bflo(z2.x)), O[d][4 * g + 1] * rstd * siluf_(bfhi(z2.x)));
;                 o.y = pk2(O[d][4 * g + 2] * rstd * siluf_(bflo(z2.y)), O[d][4 * g + 3] * rstd * siluf_(bfhi(z2.y)));
;                 *(u32x2*)zp = o;
;                 if (g == 3) __builtin_amdgcn_sched_barrier(0);
;             }
	v_mov_b32_e32 v32, v26
	v_mov_b32_e32 v33, v28
	v_mov_b32_e32 v28, v27
	v_pk_mul_f32 v[32:33], v[134:135], v[32:33]
	v_pk_mul_f32 v[2:3], v[134:135], v[28:29]
	v_pk_fma_f32 v[100:101], v[20:21], v[132:133], v[32:33] op_sel_hi:[1,0,1] neg_lo:[0,0,1] neg_hi:[0,0,1]
	v_pk_fma_f32 v[20:21], v[4:5], v[132:133], v[2:3] op_sel_hi:[1,0,1] neg_lo:[0,0,1] neg_hi:[0,0,1]
	ds_read_b128 v[26:29], v1 offset:448
	v_pk_mul_f32 v[2:3], v[20:21], v[20:21]
	s_nop 0
	v_pk_fma_f32 v[2:3], v[100:101], v[100:101], v[2:3]
	s_nop 0
	v_pk_add_f32 v[114:115], v[2:3], v[2:3] op_sel:[0,1] op_sel_hi:[1,0]
	v_mov_b32_e32 v2, v6
	s_waitcnt lgkmcnt(1)
	v_mov_b32_e32 v3, v42
	v_pk_mul_f32 v[102:103], v[2:3], v[132:133]
	v_pk_mul_f32 v[2:3], v[134:135], v[44:45]
	v_mov_b32_e32 v42, v7
	v_pk_fma_f32 v[8:9], v[8:9], v[132:133], v[2:3] op_sel_hi:[1,0,1] neg_lo:[0,0,1] neg_hi:[0,0,1]
	v_mov_b32_e32 v6, v10
	v_mul_f32_e32 v2, v9, v9
	v_pk_fma_f32 v[104:105], v[8:9], v[8:9], v[2:3] op_sel_hi:[1,1,0]
	ds_read_b128 v[2:5], v1 offset:480
	s_waitcnt lgkmcnt(1)
	v_mov_b32_e32 v7, v26
	v_pk_mul_f32 v[58:59], v[6:7], v[132:133]
	v_mov_b32_e32 v6, v12
	v_mov_b32_e32 v7, v28
	v_mov_b32_e32 v26, v11
	v_pk_mul_f32 v[60:61], v[6:7], v[132:133]
	v_mov_b32_e32 v28, v13
	v_mov_b32_e32 v6, v14
	s_waitcnt lgkmcnt(0)
	v_mov_b32_e32 v7, v2
	v_mul_f32_e32 v2, v2, v133
	v_mov_b32_e32 v10, v16
	v_mov_b32_e32 v11, v4
	v_mov_b32_e32 v4, v17
	v_pk_mul_f32 v[106:107], v[42:43], v[132:133]
	v_pk_mul_f32 v[48:49], v[26:27], v[132:133]
	v_pk_mul_f32 v[64:65], v[28:29], v[132:133]
	v_pk_fma_f32 v[6:7], v[6:7], v[132:133], v[2:3] op_sel_hi:[1,1,0] neg_lo:[0,0,1] neg_hi:[0,0,1]
	v_pk_mul_f32 v[26:27], v[10:11], v[132:133]
	v_pk_mul_f32 v[28:29], v[4:5], v[132:133]
	s_waitcnt vmcnt(15)
	v_lshlrev_b32_e32 v16, 16, v126
	v_and_b32_e32 v17, 0xffff0000, v126
	v_mul_f32_e32 v1, 0xbfb8aa3b, v16
	v_exp_f32_e32 v1, v1
	v_mul_f32_e32 v2, 0xbfb8aa3b, v17
	v_exp_f32_e32 v7, v2
	v_pk_mul_f32 v[10:11], v[134:135], v[68:69]
	v_add_f32_e32 v1, 1.0, v1
	v_pk_fma_f32 v[10:11], v[52:53], v[132:133], v[10:11] op_sel_hi:[1,0,1] neg_lo:[0,0,1] neg_hi:[0,0,1]
	v_rcp_f32_e32 v32, v1
	v_add_f32_e32 v1, 1.0, v7
	v_pk_mul_f32 v[12:13], v[134:135], v[66:67]
	v_lshlrev_b32_e32 v66, 16, v127
	v_mul_f32_e32 v2, v11, v11
	v_rcp_f32_e32 v33, v1
	v_and_b32_e32 v67, 0xffff0000, v127
	v_mul_f32_e32 v1, 0xbfb8aa3b, v66
	v_pk_fma_f32 v[42:43], v[10:11], v[10:11], v[2:3] op_sel_hi:[1,1,0]
	v_exp_f32_e32 v1, v1
	v_mul_f32_e32 v2, 0xbfb8aa3b, v67
	v_exp_f32_e32 v2, v2
	v_pk_fma_f32 v[12:13], v[50:51], v[132:133], v[12:13] op_sel_hi:[1,0,1] neg_lo:[0,0,1] neg_hi:[0,0,1]
	v_mov_b32_e32 v51, v133
	v_mov_b32_e32 v50, v13
	v_pk_mov_b32 v[52:53], v[12:13], v[54:55] op_sel:[1,0]
	v_pk_mul_f32 v[16:17], v[32:33], v[16:17]
	v_mov_b32_e32 v32, v12
	v_mov_b32_e32 v33, v62
	v_mov_b32_e32 v44, v12
	v_mov_b32_e32 v45, v132
	v_pk_mul_f32 v[50:51], v[50:51], v[52:53]
	v_add_f32_e32 v1, 1.0, v1
	v_pk_fma_f32 v[52:53], v[32:33], v[44:45], v[50:51]
	v_pk_fma_f32 v[126:127], v[32:33], v[44:45], v[50:51] neg_lo:[0,0,1] neg_hi:[0,0,1]
	v_rcp_f32_e32 v32, v1
	v_add_f32_e32 v1, 1.0, v2
	v_rcp_f32_e32 v33, v1
	v_pk_add_f32 v[50:51], v[52:53], v[42:43]
	v_pk_mul_f32 v[42:43], v[126:127], v[126:127]
	v_mov_b32_e32 v53, v133
	v_mov_b32_e32 v51, v43
	v_pk_mul_f32 v[42:43], v[32:33], v[66:67]
	v_mov_b32_e32 v32, v180
	v_mov_b32_e32 v33, v184
	v_mov_b32_e32 v184, v181
	v_pk_add_f32 v[44:45], v[32:33], v[184:185] neg_lo:[0,1] neg_hi:[0,1]
	v_mov_b32_e32 v33, v132
	v_mov_b32_e32 v52, v45
	v_mov_b32_e32 v54, v45
	v_mov_b32_e32 v62, v44
	v_mov_b32_e32 v32, v44
	v_pk_mul_f32 v[52:53], v[52:53], v[54:55]
	s_waitcnt vmcnt(14)
	v_lshlrev_b32_e32 v68, 16, v111
	v_pk_fma_f32 v[54:55], v[62:63], v[32:33], v[52:53]
	v_pk_fma_f32 v[32:33], v[62:63], v[32:33], v[52:53] neg_lo:[0,0,1] neg_hi:[0,0,1]
	v_pk_add_f32 v[52:53], v[54:55], v[182:183]
	v_lshlrev_b32_e32 v54, 16, v110
	v_and_b32_e32 v55, 0xffff0000, v110
	v_mul_f32_e32 v1, 0xbfb8aa3b, v54
	v_exp_f32_e32 v1, v1
	v_mul_f32_e32 v2, 0xbfb8aa3b, v55
	v_exp_f32_e32 v2, v2
	v_and_b32_e32 v69, 0xffff0000, v111
	v_add_f32_e32 v1, 1.0, v1
	v_rcp_f32_e32 v66, v1
	v_add_f32_e32 v1, 1.0, v2
	v_mul_f32_e32 v2, 0xbfb8aa3b, v68
	v_exp_f32_e32 v2, v2
	v_mul_f32_e32 v7, 0xbfb8aa3b, v69
	v_exp_f32_e32 v7, v7
	v_rcp_f32_e32 v67, v1
	s_lshl_b32 s54, s10, 1
	v_pk_mul_f32 v[62:63], v[32:33], v[32:33]
	v_lshl_add_u64 v[4:5], v[136:137], 0, s[54:55]
	v_mov_b32_e32 v131, v99
	v_add_f32_e32 v1, 1.0, v2
	v_mov_b32_e32 v53, v63
	v_lshl_add_u64 v[4:5], v[4:5], 0, v[130:131]
	v_lshl_add_u64 v[4:5], v[4:5], 0, v[130:131]
	v_rcp_f32_e32 v110, v1
	v_add_f32_e32 v1, 1.0, v7
	v_pk_add_f32 v[130:131], v[50:51], v[52:53]
	v_pk_mul_f32 v[52:53], v[66:67], v[54:55]
	s_waitcnt vmcnt(13)
	v_lshlrev_b32_e32 v66, 16, v108
	v_rcp_f32_e32 v111, v1
	v_and_b32_e32 v67, 0xffff0000, v108
	v_mul_f32_e32 v1, 0xbfb8aa3b, v66
	v_exp_f32_e32 v1, v1
	v_mul_f32_e32 v2, 0xbfb8aa3b, v67
	v_exp_f32_e32 v2, v2
	v_lshlrev_b32_e32 v108, 16, v109
	v_add_f32_e32 v1, 1.0, v1
	v_pk_mul_f32 v[54:55], v[110:111], v[68:69]
	v_rcp_f32_e32 v68, v1
	v_add_f32_e32 v1, 1.0, v2
	v_and_b32_e32 v109, 0xffff0000, v109
	v_mul_f32_e32 v2, 0xbfb8aa3b, v108
	v_exp_f32_e32 v2, v2
	v_mul_f32_e32 v7, 0xbfb8aa3b, v109
	v_exp_f32_e32 v7, v7
	v_rcp_f32_e32 v69, v1
	v_add_f32_e32 v1, 1.0, v2
	v_rcp_f32_e32 v136, v1
	v_add_f32_e32 v1, 1.0, v7
	v_mov_b32_e32 v50, v176
	v_mov_b32_e32 v51, v178
	v_mov_b32_e32 v178, v177
	v_rcp_f32_e32 v137, v1
	v_pk_add_f32 v[50:51], v[50:51], v[178:179] neg_lo:[0,1] neg_hi:[0,1]
	v_pk_mul_f32 v[68:69], v[68:69], v[66:67]
	v_mov_b32_e32 v66, v168
	v_mov_b32_e32 v67, v172
	v_mov_b32_e32 v172, v169
	v_pk_mul_f32 v[110:111], v[50:51], v[50:51]
	v_mov_b32_e32 v62, v174
	v_mov_b32_e32 v63, v170
	v_mov_b32_e32 v170, v175
	v_pk_add_f32 v[66:67], v[66:67], v[172:173] neg_lo:[0,1] neg_hi:[0,1]
	v_pk_add_f32 v[62:63], v[62:63], v[170:171] neg_lo:[0,1] neg_hi:[0,1]
	v_mov_b32_e32 v110, v111
	v_mov_b32_e32 v111, v67
	v_pk_mul_f32 v[170:171], v[62:63], v[62:63]
	v_pk_mul_f32 v[108:109], v[136:137], v[108:109]
	v_pk_fma_f32 v[110:111], v[50:51], v[50:51], v[110:111]
	v_pk_mul_f32 v[136:137], v[66:67], v[66:67]
	s_waitcnt vmcnt(11)
; DI unsigned pk2(float a, float b) { f32x2 v = {a, b}; return __builtin_bit_cast(unsigned, __builtin_convertvector(v, bfv2)); }
; DI float bflo(unsigned u) { return __uint_as_float(u << 16); }
; DI float bfhi(unsigned u) { return __uint_as_float(u & 0xffff0000u); }
; DI float xor32_sum(float x) { auto r = __builtin_amdgcn_permlane32_swap(__float_as_uint(x), __float_as_uint(x), false, false); return __uint_as_float(r[0]) + __uint_as_float(r[1]); }
; DI float siluf_(float z) { return z * __builtin_amdgcn_rcpf(1.f + __expf(-z)); }
; DI void attn_item(const Params& p, unsigned char* lds, int b, int hd, int qb, float lam) {
;     ...
;         for (int d = 0; d < 4; ++d) {
; #pragma unroll
;             for (int g = 0; g < 4; ++g) {
;                 const f32x4 t = *(const f32x4*)(ex + (rt * 32 + l31) * 132 + d * 32 + 8 * g + 4 * h);
;                 const float o0 = O[d][4 * g] * linv - lam * t.x, o1 = O[d][4 * g + 1] * linv - lam * t.y;
;                 const float o2 = O[d][4 * g + 2] * linv - lam * t.z, o3 = O[d][4 * g + 3] * linv - lam * t.w;
;                 O[d][4 * g] = o0; O[d][4 * g + 1] = o1; O[d][4 * g + 2] = o2; O[d][4 * g + 3] = o3;
;                 ss += (o0 * o0 + o1 * o1) + (o2 * o2 + o3 * o3);
;             }
;             __builtin_amdgcn_sched_barrier(0);
;         }
;         ss = xor32_sum(ss);
;         const float rstd = 1.0f / sqrtf(ss * (1.0f / 128.0f) + EPS);
; #pragma unroll
;         for (int d = 0; d < 4; ++d)
; #pragma unroll
;             for (int g = 0; g < 4; ++g) {
;                 bf16_t* zp = az + grow * 1024 + hd * 128 + d * 32 + 8 * g + 4 * h;
;                 const u32x2 z2 = zz[d][g];
;                 u32x2 o;
;                 o.x = pk2(O[d][4 * g] * rstd * siluf_(bflo(z2.x)), O[d][4 * g + 1] * rstd * siluf_(bfhi(z2.x)));
;                 o.y = pk2(O[d][4 * g + 2] * rstd * siluf_(bflo(z2.y)), O[d][4 * g + 3] * rstd * siluf_(bfhi(z2.y)));
	v_lshlrev_b32_e32 v126, 16, v94
	v_mov_b32_e32 v111, v137
	v_pk_mov_b32 v[136:137], v[170:171], v[66:67] op_sel:[1,0]
	v_mov_b32_e32 v32, v127
	v_pk_fma_f32 v[168:169], v[62:63], v[62:63], v[136:137]
	v_pk_mul_f32 v[136:137], v[66:67], v[136:137] op_sel_hi:[0,1]
	v_mov_b32_e32 v169, v137
	v_pk_add_f32 v[110:111], v[168:169], v[110:111]
	v_and_b32_e32 v127, 0xffff0000, v94
	v_pk_add_f32 v[110:111], v[130:131], v[110:111]
	v_lshlrev_b32_e32 v130, 16, v96
	v_and_b32_e32 v131, 0xffff0000, v96
	v_mul_f32_e32 v1, 0xbfb8aa3b, v130
	v_exp_f32_e32 v1, v1
	v_mul_f32_e32 v2, 0xbfb8aa3b, v131
	v_exp_f32_e32 v2, v2
	v_pk_add_f32 v[110:111], v[110:111], v[110:111] op_sel:[0,1] op_sel_hi:[1,0]
	v_add_f32_e32 v1, 1.0, v1
	v_pk_add_f32 v[166:167], v[110:111], v[166:167]
	v_lshlrev_b32_e32 v110, 16, v97
	v_rcp_f32_e32 v96, v1
	v_add_f32_e32 v1, 1.0, v2
	v_and_b32_e32 v111, 0xffff0000, v97
	v_mul_f32_e32 v2, 0xbfb8aa3b, v110
	v_exp_f32_e32 v2, v2
	v_mul_f32_e32 v7, 0xbfb8aa3b, v111
	v_exp_f32_e32 v7, v7
	v_rcp_f32_e32 v97, v1
	v_add_f32_e32 v1, 1.0, v2
	v_rcp_f32_e32 v136, v1
	v_add_f32_e32 v1, 1.0, v7
	v_rcp_f32_e32 v137, v1
	v_mul_f32_e32 v1, 0xbfb8aa3b, v126
	v_exp_f32_e32 v1, v1
	v_mul_f32_e32 v2, 0xbfb8aa3b, v127
	v_exp_f32_e32 v2, v2
	v_pk_mul_f32 v[110:111], v[136:137], v[110:111]
	v_add_f32_e32 v1, 1.0, v1
	v_lshlrev_b32_e32 v136, 16, v95
	v_pk_mul_f32 v[96:97], v[96:97], v[130:131]
	v_rcp_f32_e32 v130, v1
	v_add_f32_e32 v1, 1.0, v2
	v_and_b32_e32 v137, 0xffff0000, v95
	v_mul_f32_e32 v2, 0xbfb8aa3b, v136
	v_exp_f32_e32 v2, v2
	v_mul_f32_e32 v7, 0xbfb8aa3b, v137
	v_exp_f32_e32 v7, v7
	v_rcp_f32_e32 v131, v1
	v_add_f32_e32 v1, 1.0, v2
	v_rcp_f32_e32 v168, v1
	v_add_f32_e32 v1, 1.0, v7
	v_rcp_f32_e32 v169, v1
	v_pk_mul_f32 v[126:127], v[130:131], v[126:127]
	v_mov_b32_e32 v94, v158
	v_mov_b32_e32 v95, v56
	v_pk_mul_f32 v[130:131], v[168:169], v[136:137]
	v_mov_b32_e32 v136, v160
	v_mov_b32_e32 v137, v164
	v_mov_b32_e32 v164, v161
	v_pk_add_f32 v[136:137], v[136:137], v[164:165] neg_lo:[0,1] neg_hi:[0,1]
	v_mov_b32_e32 v161, v133
	v_mov_b32_e32 v160, v137
	v_mov_b32_e32 v34, v137
	v_mov_b32_e32 v56, v159
	v_mov_b32_e32 v46, v136
	v_mov_b32_e32 v158, v136
	v_mov_b32_e32 v159, v132
	v_pk_mul_f32 v[34:35], v[160:161], v[34:35]
	v_mul_f32_e32 v167, v40, v40
	v_pk_fma_f32 v[160:161], v[46:47], v[158:159], v[34:35]
	v_pk_fma_f32 v[158:159], v[46:47], v[158:159], v[34:35] neg_lo:[0,0,1] neg_hi:[0,0,1]
	s_waitcnt vmcnt(10)
	v_lshlrev_b32_e32 v46, 16, v92
	v_and_b32_e32 v47, 0xffff0000, v92
	v_mul_f32_e32 v1, 0xbfb8aa3b, v46
	v_exp_f32_e32 v1, v1
	v_mul_f32_e32 v2, 0xbfb8aa3b, v47
	v_exp_f32_e32 v2, v2
	v_pk_add_f32 v[34:35], v[160:161], v[162:163]
	v_add_f32_e32 v1, 1.0, v1
	v_lshlrev_b32_e32 v162, 16, v93
	v_rcp_f32_e32 v92, v1
	v_add_f32_e32 v1, 1.0, v2
	v_and_b32_e32 v163, 0xffff0000, v93
	v_mul_f32_e32 v2, 0xbfb8aa3b, v162
	v_exp_f32_e32 v2, v2
	v_mul_f32_e32 v7, 0xbfb8aa3b, v163
	v_exp_f32_e32 v7, v7
	v_rcp_f32_e32 v93, v1
	v_add_f32_e32 v1, 1.0, v2
	v_rcp_f32_e32 v164, v1
	v_add_f32_e32 v1, 1.0, v7
	v_rcp_f32_e32 v165, v1
	v_pk_mul_f32 v[46:47], v[92:93], v[46:47]
	v_pk_mul_f32 v[160:161], v[158:159], v[158:159]
	s_waitcnt vmcnt(7)
	v_lshlrev_b32_e32 v158, 16, v87
	v_pk_mul_f32 v[92:93], v[164:165], v[162:163]
	v_lshlrev_b32_e32 v162, 16, v90
	v_and_b32_e32 v163, 0xffff0000, v90
	v_mul_f32_e32 v1, 0xbfb8aa3b, v162
	v_exp_f32_e32 v1, v1
	v_mul_f32_e32 v2, 0xbfb8aa3b, v163
	v_exp_f32_e32 v2, v2
	v_mov_b32_e32 v35, v161
	v_pk_add_f32 v[160:161], v[166:167], v[34:35]
	v_mov_b32_e32 v34, v154
	v_mov_b32_e32 v35, v156
	v_mov_b32_e32 v156, v155
	v_mov_b32_e32 v154, v152
	v_mov_b32_e32 v155, v144
	v_mov_b32_e32 v144, v153
	v_add_f32_e32 v1, 1.0, v1
	v_lshlrev_b32_e32 v164, 16, v91
	v_pk_add_f32 v[34:35], v[34:35], v[156:157] neg_lo:[0,1] neg_hi:[0,1]
	v_rcp_f32_e32 v152, v1
	v_add_f32_e32 v1, 1.0, v2
	v_and_b32_e32 v165, 0xffff0000, v91
	v_mul_f32_e32 v2, 0xbfb8aa3b, v164
	v_pk_add_f32 v[90:91], v[154:155], v[144:145] neg_lo:[0,1] neg_hi:[0,1]
	v_mov_b32_e32 v144, v148
	v_mov_b32_e32 v145, v150
	v_mov_b32_e32 v150, v149
	v_pk_mul_f32 v[156:157], v[34:35], v[34:35]
	v_exp_f32_e32 v2, v2
	v_mul_f32_e32 v7, 0xbfb8aa3b, v165
	v_pk_add_f32 v[144:145], v[144:145], v[150:151] neg_lo:[0,1] neg_hi:[0,1]
	v_exp_f32_e32 v7, v7
	v_mov_b32_e32 v148, v157
	v_mov_b32_e32 v149, v145
	v_pk_mul_f32 v[168:169], v[90:91], v[90:91]
	v_pk_fma_f32 v[148:149], v[34:35], v[34:35], v[148:149]
	v_pk_mul_f32 v[150:151], v[144:145], v[144:145]
	v_rcp_f32_e32 v153, v1
	v_mov_b32_e32 v149, v151
	v_pk_mov_b32 v[150:151], v[168:169], v[144:145] op_sel:[1,0]
	v_add_f32_e32 v1, 1.0, v2
	v_pk_fma_f32 v[156:157], v[90:91], v[90:91], v[150:151]
	v_pk_mul_f32 v[150:151], v[144:145], v[150:151] op_sel_hi:[0,1]
	v_rcp_f32_e32 v166, v1
	v_add_f32_e32 v1, 1.0, v7
	v_lshlrev_b32_e32 v150, 16, v88
	v_rcp_f32_e32 v167, v1
	v_mov_b32_e32 v157, v151
	v_and_b32_e32 v151, 0xffff0000, v88
	v_mul_f32_e32 v1, 0xbfb8aa3b, v150
	v_exp_f32_e32 v1, v1
	v_mul_f32_e32 v2, 0xbfb8aa3b, v151
	v_pk_add_f32 v[148:149], v[156:157], v[148:149]
	v_exp_f32_e32 v2, v2
	v_pk_add_f32 v[148:149], v[160:161], v[148:149]
	v_add_f32_e32 v1, 1.0, v1
	v_pk_add_f32 v[148:149], v[148:149], v[148:149] op_sel:[0,1] op_sel_hi:[1,0]
	v_rcp_f32_e32 v88, v1
	v_pk_add_f32 v[156:157], v[148:149], v[146:147]
	v_lshlrev_b32_e32 v146, 16, v89
	v_add_f32_e32 v1, 1.0, v2
	v_and_b32_e32 v147, 0xffff0000, v89
	v_mul_f32_e32 v2, 0xbfb8aa3b, v146
	v_exp_f32_e32 v2, v2
	v_mul_f32_e32 v7, 0xbfb8aa3b, v147
	v_exp_f32_e32 v7, v7
	v_rcp_f32_e32 v89, v1
	v_add_f32_e32 v1, 1.0, v2
	v_rcp_f32_e32 v148, v1
	v_add_f32_e32 v1, 1.0, v7
	v_rcp_f32_e32 v149, v1
	v_pk_mul_f32 v[88:89], v[88:89], v[150:151]
	v_mov_b32_e32 v41, v159
	v_and_b32_e32 v159, 0xffff0000, v87
	v_pk_mul_f32 v[146:147], v[148:149], v[146:147]
	v_lshlrev_b32_e32 v148, 16, v86
	v_mul_f32_e32 v1, 0xbfb8aa3b, v148
	v_and_b32_e32 v149, 0xffff0000, v86
	v_exp_f32_e32 v1, v1
	v_mul_f32_e32 v2, 0xbfb8aa3b, v149
	v_exp_f32_e32 v2, v2
	v_mul_f32_e32 v7, 0xbfb8aa3b, v159
	v_add_f32_e32 v1, 1.0, v1
	v_rcp_f32_e32 v150, v1
	v_add_f32_e32 v1, 1.0, v2
	v_rcp_f32_e32 v151, v1
	v_mul_f32_e32 v2, 0xbfb8aa3b, v158
	v_exp_f32_e32 v2, v2
	v_exp_f32_e32 v7, v7
	v_pk_mul_f32 v[148:149], v[150:151], v[148:149]
	v_mov_b32_e32 v150, v138
	v_mov_b32_e32 v151, v142
	v_mov_b32_e32 v142, v139
	v_pk_add_f32 v[138:139], v[150:151], v[142:143] neg_lo:[0,1] neg_hi:[0,1]
	v_mov_b32_e32 v151, v133
	v_mov_b32_e32 v150, v139
	v_mov_b32_e32 v18, v139
	v_add_f32_e32 v1, 1.0, v2
	v_mov_b32_e32 v30, v138
	v_mov_b32_e32 v142, v138
	v_mov_b32_e32 v143, v132
	v_pk_mul_f32 v[18:19], v[150:151], v[18:19]
	v_rcp_f32_e32 v160, v1
	v_add_f32_e32 v1, 1.0, v7
	v_pk_fma_f32 v[150:151], v[30:31], v[142:143], v[18:19]
	v_pk_fma_f32 v[142:143], v[30:31], v[142:143], v[18:19] neg_lo:[0,0,1] neg_hi:[0,0,1]
	s_waitcnt vmcnt(6)
; DI unsigned pk2(float a, float b) { f32x2 v = {a, b}; return __builtin_bit_cast(unsigned, __builtin_convertvector(v, bfv2)); }
; DI float bflo(unsigned u) { return __uint_as_float(u << 16); }
; DI float bfhi(unsigned u) { return __uint_as_float(u & 0xffff0000u); }
; DI float xor32_sum(float x) { auto r = __builtin_amdgcn_permlane32_swap(__float_as_uint(x), __float_as_uint(x), false, false); return __uint_as_float(r[0]) + __uint_as_float(r[1]); }
; DI float siluf_(float z) { return z * __builtin_amdgcn_rcpf(1.f + __expf(-z)); }
; DI void attn_item(const Params& p, unsigned char* lds, int b, int hd, int qb, float lam) {
;     ...
;         for (int d = 0; d < 4; ++d) {
; #pragma unroll
;             for (int g = 0; g < 4; ++g) {
;                 const f32x4 t = *(const f32x4*)(ex + (rt * 32 + l31) * 132 + d * 32 + 8 * g + 4 * h);
;                 const float o0 = O[d][4 * g] * linv - lam * t.x, o1 = O[d][4 * g + 1] * linv - lam * t.y;
;                 const float o2 = O[d][4 * g + 2] * linv - lam * t.z, o3 = O[d][4 * g + 3] * linv - lam * t.w;
;                 O[d][4 * g] = o0; O[d][4 * g + 1] = o1; O[d][4 * g + 2] = o2; O[d][4 * g + 3] = o3;
;                 ss += (o0 * o0 + o1 * o1) + (o2 * o2 + o3 * o3);
;             }
;             __builtin_amdgcn_sched_barrier(0);
;         }
;         ss = xor32_sum(ss);
;         const float rstd = 1.0f / sqrtf(ss * (1.0f / 128.0f) + EPS);
; #pragma unroll
;         for (int d = 0; d < 4; ++d)
; #pragma unroll
;             for (int g = 0; g < 4; ++g) {
;                 bf16_t* zp = az + grow * 1024 + hd * 128 + d * 32 + 8 * g + 4 * h;
;                 const u32x2 z2 = zz[d][g];
;                 u32x2 o;
;                 o.x = pk2(O[d][4 * g] * rstd * siluf_(bflo(z2.x)), O[d][4 * g + 1] * rstd * siluf_(bfhi(z2.x)));
;                 o.y = pk2(O[d][4 * g + 2] * rstd * siluf_(bflo(z2.y)), O[d][4 * g + 3] * rstd * siluf_(bfhi(z2.y)));
	v_lshlrev_b32_e32 v30, 16, v84
	v_rcp_f32_e32 v161, v1
	v_and_b32_e32 v31, 0xffff0000, v84
	v_mul_f32_e32 v1, 0xbfb8aa3b, v30
	v_exp_f32_e32 v1, v1
	v_mul_f32_e32 v2, 0xbfb8aa3b, v31
	v_exp_f32_e32 v2, v2
	v_pk_add_f32 v[18:19], v[150:151], v[140:141]
	v_add_f32_e32 v1, 1.0, v1
	v_lshlrev_b32_e32 v150, 16, v85
	v_rcp_f32_e32 v84, v1
	v_add_f32_e32 v1, 1.0, v2
	v_and_b32_e32 v151, 0xffff0000, v85
	v_mul_f32_e32 v2, 0xbfb8aa3b, v150
	v_exp_f32_e32 v2, v2
	v_mul_f32_e32 v7, 0xbfb8aa3b, v151
	v_exp_f32_e32 v7, v7
	v_rcp_f32_e32 v85, v1
	v_add_f32_e32 v1, 1.0, v2
	v_mov_b32_e32 v86, v128
	v_mov_b32_e32 v87, v36
	v_mov_b32_e32 v36, v129
	v_pk_mul_f32 v[128:129], v[160:161], v[158:159]
	v_rcp_f32_e32 v158, v1
	v_add_f32_e32 v1, 1.0, v7
	v_rcp_f32_e32 v159, v1
	v_pk_mul_f32 v[30:31], v[84:85], v[30:31]
	v_pk_mul_f32 v[140:141], v[142:143], v[142:143]
	v_mul_f32_e32 v157, v24, v24
	v_pk_mul_f32 v[84:85], v[158:159], v[150:151]
	s_waitcnt vmcnt(5)
	v_lshlrev_b32_e32 v150, 16, v80
	v_and_b32_e32 v151, 0xffff0000, v80
	v_mul_f32_e32 v1, 0xbfb8aa3b, v150
	v_exp_f32_e32 v1, v1
	v_mul_f32_e32 v2, 0xbfb8aa3b, v151
	v_exp_f32_e32 v2, v2
	v_mov_b32_e32 v19, v141
	v_pk_add_f32 v[140:141], v[156:157], v[18:19]
	v_mov_b32_e32 v18, v122
	v_mov_b32_e32 v19, v124
	v_mov_b32_e32 v124, v123
	v_mov_b32_e32 v122, v120
	v_mov_b32_e32 v123, v112
	v_mov_b32_e32 v112, v121
	v_add_f32_e32 v1, 1.0, v1
	v_lshlrev_b32_e32 v156, 16, v81
	v_pk_add_f32 v[18:19], v[18:19], v[124:125] neg_lo:[0,1] neg_hi:[0,1]
	v_rcp_f32_e32 v120, v1
	v_add_f32_e32 v1, 1.0, v2
	v_and_b32_e32 v157, 0xffff0000, v81
	v_mul_f32_e32 v2, 0xbfb8aa3b, v156
	v_pk_add_f32 v[80:81], v[122:123], v[112:113] neg_lo:[0,1] neg_hi:[0,1]
	v_mov_b32_e32 v112, v116
	v_mov_b32_e32 v113, v118
	v_mov_b32_e32 v118, v117
	v_pk_mul_f32 v[124:125], v[18:19], v[18:19]
	v_exp_f32_e32 v2, v2
	v_mul_f32_e32 v7, 0xbfb8aa3b, v157
	v_pk_add_f32 v[112:113], v[112:113], v[118:119] neg_lo:[0,1] neg_hi:[0,1]
	v_exp_f32_e32 v7, v7
	v_mov_b32_e32 v116, v125
	v_mov_b32_e32 v117, v113
	v_pk_mul_f32 v[160:161], v[80:81], v[80:81]
	v_pk_fma_f32 v[116:117], v[18:19], v[18:19], v[116:117]
	v_pk_mul_f32 v[118:119], v[112:113], v[112:113]
	v_rcp_f32_e32 v121, v1
	v_mov_b32_e32 v117, v119
	v_pk_mov_b32 v[118:119], v[160:161], v[112:113] op_sel:[1,0]
	v_add_f32_e32 v1, 1.0, v2
	v_pk_fma_f32 v[124:125], v[80:81], v[80:81], v[118:119]
	v_pk_mul_f32 v[118:119], v[112:113], v[118:119] op_sel_hi:[0,1]
	v_rcp_f32_e32 v158, v1
	v_add_f32_e32 v1, 1.0, v7
	s_waitcnt vmcnt(4)
	v_lshlrev_b32_e32 v118, 16, v78
	v_rcp_f32_e32 v159, v1
	v_mov_b32_e32 v125, v119
	v_and_b32_e32 v119, 0xffff0000, v78
	v_mul_f32_e32 v1, 0xbfb8aa3b, v118
	v_exp_f32_e32 v1, v1
	v_mul_f32_e32 v2, 0xbfb8aa3b, v119
	v_pk_add_f32 v[116:117], v[124:125], v[116:117]
	v_exp_f32_e32 v2, v2
	v_pk_add_f32 v[116:117], v[140:141], v[116:117]
	v_add_f32_e32 v1, 1.0, v1
	v_pk_add_f32 v[116:117], v[116:117], v[116:117] op_sel:[0,1] op_sel_hi:[1,0]
	v_rcp_f32_e32 v78, v1
	v_pk_add_f32 v[124:125], v[116:117], v[114:115]
	v_lshlrev_b32_e32 v114, 16, v79
	v_add_f32_e32 v1, 1.0, v2
	v_and_b32_e32 v115, 0xffff0000, v79
	v_mul_f32_e32 v2, 0xbfb8aa3b, v114
	v_exp_f32_e32 v2, v2
	v_mul_f32_e32 v7, 0xbfb8aa3b, v115
	v_exp_f32_e32 v7, v7
	v_rcp_f32_e32 v79, v1
	v_add_f32_e32 v1, 1.0, v2
	v_rcp_f32_e32 v116, v1
	v_add_f32_e32 v1, 1.0, v7
	v_rcp_f32_e32 v117, v1
	v_pk_mul_f32 v[78:79], v[78:79], v[118:119]
	s_waitcnt vmcnt(3)
	v_lshlrev_b32_e32 v140, 16, v77
	v_and_b32_e32 v141, 0xffff0000, v77
	v_pk_mul_f32 v[114:115], v[116:117], v[114:115]
	v_lshlrev_b32_e32 v116, 16, v76
	v_mul_f32_e32 v1, 0xbfb8aa3b, v116
	v_and_b32_e32 v117, 0xffff0000, v76
	v_exp_f32_e32 v1, v1
	v_mul_f32_e32 v2, 0xbfb8aa3b, v117
	v_exp_f32_e32 v2, v2
	v_mul_f32_e32 v7, 0xbfb8aa3b, v141
	v_add_f32_e32 v1, 1.0, v1
	v_rcp_f32_e32 v118, v1
	v_add_f32_e32 v1, 1.0, v2
	v_rcp_f32_e32 v119, v1
	v_mul_f32_e32 v2, 0xbfb8aa3b, v140
	v_exp_f32_e32 v2, v2
	v_exp_f32_e32 v7, v7
	v_pk_mul_f32 v[116:117], v[118:119], v[116:117]
	v_mov_b32_e32 v118, v102
	v_mov_b32_e32 v119, v106
	v_mov_b32_e32 v106, v103
	v_pk_add_f32 v[102:103], v[118:119], v[106:107] neg_lo:[0,1] neg_hi:[0,1]
	v_add_f32_e32 v1, 1.0, v2
	v_mov_b32_e32 v107, v132
	v_mov_b32_e32 v132, v103
	v_mov_b32_e32 v2, v103
	v_mov_b32_e32 v14, v102
	v_mov_b32_e32 v106, v102
	v_pk_mul_f32 v[2:3], v[132:133], v[2:3]
	v_rcp_f32_e32 v142, v1
	v_pk_fma_f32 v[118:119], v[14:15], v[106:107], v[2:3]
	v_pk_fma_f32 v[2:3], v[14:15], v[106:107], v[2:3] neg_lo:[0,0,1] neg_hi:[0,0,1]
	v_pk_add_f32 v[14:15], v[118:119], v[104:105]
	v_pk_mul_f32 v[104:105], v[2:3], v[2:3]
	v_add_f32_e32 v1, 1.0, v7
	s_waitcnt vmcnt(2)
	v_lshlrev_b32_e32 v104, 16, v74
	v_mov_b32_e32 v25, v143
	v_rcp_f32_e32 v143, v1
	v_mov_b32_e32 v15, v105
	v_and_b32_e32 v105, 0xffff0000, v74
	v_mul_f32_e32 v1, 0xbfb8aa3b, v104
	v_exp_f32_e32 v1, v1
	v_mul_f32_e32 v2, 0xbfb8aa3b, v105
	v_exp_f32_e32 v2, v2
	v_mul_f32_e32 v125, v6, v6
	v_add_f32_e32 v1, 1.0, v1
	v_pk_add_f32 v[106:107], v[124:125], v[14:15]
	v_rcp_f32_e32 v14, v1
	v_add_f32_e32 v1, 1.0, v2
	v_lshlrev_b32_e32 v74, 16, v75
	v_rcp_f32_e32 v15, v1
	v_and_b32_e32 v75, 0xffff0000, v75
	v_mul_f32_e32 v1, 0xbfb8aa3b, v74
	v_exp_f32_e32 v1, v1
	v_mul_f32_e32 v2, 0xbfb8aa3b, v75
	v_exp_f32_e32 v2, v2
	v_pk_mul_f32 v[104:105], v[14:15], v[104:105]
	v_mov_b32_e32 v14, v60
	v_mov_b32_e32 v15, v64
	v_mov_b32_e32 v64, v61
	v_mov_b32_e32 v76, v100
	v_mov_b32_e32 v77, v20
	v_mov_b32_e32 v20, v101
	v_pk_mul_f32 v[100:101], v[142:143], v[140:141]
	v_add_f32_e32 v1, 1.0, v1
	v_pk_add_f32 v[14:15], v[14:15], v[64:65] neg_lo:[0,1] neg_hi:[0,1]
	v_mov_b32_e32 v140, v26
	v_mov_b32_e32 v141, v28
	v_mov_b32_e32 v28, v27
	v_rcp_f32_e32 v118, v1
	v_add_f32_e32 v1, 1.0, v2
	v_pk_mul_f32 v[60:61], v[14:15], v[14:15]
	v_mov_b32_e32 v64, v58
	v_mov_b32_e32 v65, v48
	v_mov_b32_e32 v48, v59
	s_waitcnt vmcnt(1)
; DI unsigned pk2(float a, float b) { f32x2 v = {a, b}; return __builtin_bit_cast(unsigned, __builtin_convertvector(v, bfv2)); }
; DI float bflo(unsigned u) { return __uint_as_float(u << 16); }
; DI float bfhi(unsigned u) { return __uint_as_float(u & 0xffff0000u); }
; DI float xor32_sum(float x) { auto r = __builtin_amdgcn_permlane32_swap(__float_as_uint(x), __float_as_uint(x), false, false); return __uint_as_float(r[0]) + __uint_as_float(r[1]); }
; DI float siluf_(float z) { return z * __builtin_amdgcn_rcpf(1.f + __expf(-z)); }
; DI void attn_item(const Params& p, unsigned char* lds, int b, int hd, int qb, float lam) {
;     ...
;         ss = xor32_sum(ss);
;         const float rstd = 1.0f / sqrtf(ss * (1.0f / 128.0f) + EPS);
; #pragma unroll
;         for (int d = 0; d < 4; ++d)
; #pragma unroll
;             for (int g = 0; g < 4; ++g) {
;                 bf16_t* zp = az + grow * 1024 + hd * 128 + d * 32 + 8 * g + 4 * h;
;                 const u32x2 z2 = zz[d][g];
;                 u32x2 o;
;                 o.x = pk2(O[d][4 * g] * rstd * siluf_(bflo(z2.x)), O[d][4 * g + 1] * rstd * siluf_(bfhi(z2.x)));
;                 o.y = pk2(O[d][4 * g + 2] * rstd * siluf_(bflo(z2.y)), O[d][4 * g + 3] * rstd * siluf_(bfhi(z2.y)));
;                 *(u32x2*)zp = o;
	v_lshlrev_b32_e32 v58, 16, v72
	v_pk_add_f32 v[26:27], v[140:141], v[28:29] neg_lo:[0,1] neg_hi:[0,1]
	v_rcp_f32_e32 v119, v1
	v_mul_f32_e32 v1, 0xbfb8aa3b, v58
	v_pk_add_f32 v[48:49], v[64:65], v[48:49] neg_lo:[0,1] neg_hi:[0,1]
	v_mov_b32_e32 v28, v61
	v_mov_b32_e32 v29, v27
	v_exp_f32_e32 v1, v1
	v_pk_mul_f32 v[64:65], v[48:49], v[48:49]
	v_pk_fma_f32 v[28:29], v[14:15], v[14:15], v[28:29]
	v_pk_mul_f32 v[60:61], v[26:27], v[26:27]
	v_and_b32_e32 v59, 0xffff0000, v72
	v_mov_b32_e32 v29, v61
	v_pk_mov_b32 v[60:61], v[64:65], v[26:27] op_sel:[1,0]
	v_add_f32_e32 v1, 1.0, v1
	v_pk_fma_f32 v[64:65], v[48:49], v[48:49], v[60:61]
	v_pk_mul_f32 v[60:61], v[26:27], v[60:61] op_sel_hi:[0,1]
	v_mov_b32_e32 v65, v61
	v_pk_add_f32 v[28:29], v[64:65], v[28:29]
	v_rcp_f32_e32 v124, v1
	v_mul_f32_e32 v1, 0xbfb8aa3b, v59
	v_lshlrev_b32_e32 v72, 16, v73
	v_pk_add_f32 v[28:29], v[106:107], v[28:29]
	v_exp_f32_e32 v1, v1
	v_mul_f32_e32 v2, 0xbfb8aa3b, v72
	v_pk_add_f32 v[28:29], v[28:29], v[28:29] op_sel:[0,1] op_sel_hi:[1,0]
	v_exp_f32_e32 v2, v2
	v_mov_b32_e32 v7, v28
	s_nop 1
	v_permlane32_swap_b32_e32 v28, v7
	v_add_f32_e32 v7, v28, v7
	v_add_f32_e32 v1, 1.0, v1
	v_and_b32_e32 v73, 0xffff0000, v73
	v_fmamk_f32 v7, v7, 0x3c000000, v189
	s_mov_b32 s0, 0xf800000
	v_rcp_f32_e32 v125, v1
	v_add_f32_e32 v1, 1.0, v2
	v_mul_f32_e32 v2, 0xbfb8aa3b, v73
	v_mul_f32_e32 v28, 0x4f800000, v7
	v_cmp_gt_f32_e32 vcc, s0, v7
	v_exp_f32_e32 v2, v2
	v_pk_mul_f32 v[152:153], v[152:153], v[162:163]
	v_cndmask_b32_e32 v7, v7, v28, vcc
	v_sqrt_f32_e32 v60, v7
	v_rcp_f32_e32 v28, v1
	v_add_f32_e32 v1, 1.0, v2
	v_rcp_f32_e32 v29, v1
	v_add_u32_e32 v1, -1, v60
	v_fma_f32 v2, -v1, v60, v7
	v_cmp_ge_f32_e64 s[4:5], 0, v2
	v_add_u32_e32 v2, 1, v60
	v_pk_mul_f32 v[28:29], v[28:29], v[72:73]
	v_cndmask_b32_e64 v1, v60, v1, s[4:5]
	v_fma_f32 v60, -v2, v60, v7
	v_cmp_lt_f32_e64 s[4:5], 0, v60
	v_pk_mul_f32 v[154:155], v[166:167], v[164:165]
	v_pk_mul_f32 v[120:121], v[120:121], v[150:151]
	v_cndmask_b32_e64 v1, v1, v2, s[4:5]
	v_mul_f32_e32 v2, 0x37800000, v1
	v_cndmask_b32_e32 v1, v1, v2, vcc
	v_cmp_class_f32_e32 vcc, v7, v190
	v_pk_mul_f32 v[122:123], v[158:159], v[156:157]
	v_pk_mul_f32 v[60:61], v[118:119], v[74:75]
	v_cndmask_b32_e32 v1, v1, v7, vcc
	v_div_scale_f32 v2, s[4:5], v1, v1, 1.0
	v_rcp_f32_e32 v7, v2
	v_pk_mul_f32 v[58:59], v[124:125], v[58:59]
	v_fma_f32 v64, -v2, v7, 1.0
	v_fmac_f32_e32 v7, v64, v7
	v_div_scale_f32 v64, vcc, 1.0, v1, 1.0
	v_mul_f32_e32 v65, v64, v7
	v_fma_f32 v72, -v2, v65, v64
	v_fmac_f32_e32 v65, v72, v7
	v_fma_f32 v2, -v2, v65, v64
	v_div_fmas_f32 v2, v2, v7, v65
	v_div_fixup_f32 v2, v2, v1, 1.0
	v_pk_mul_f32 v[12:13], v[12:13], v[2:3] op_sel_hi:[1,0]
	v_pk_mul_f32 v[10:11], v[10:11], v[2:3] op_sel_hi:[1,0]
	v_pk_mul_f32 v[12:13], v[16:17], v[12:13]
	v_pk_mul_f32 v[10:11], v[42:43], v[10:11]
	v_cvt_pk_bf16_f32 v216, v12, v13
	v_cvt_pk_bf16_f32 v217, v10, v11
	v_pk_mul_f32 v[10:11], v[44:45], v[2:3] op_sel_hi:[1,0]
	v_pk_mul_f32 v[12:13], v[82:83], v[2:3] op_sel_hi:[1,0]
	v_pk_mul_f32 v[10:11], v[52:53], v[10:11]
	v_pk_mul_f32 v[12:13], v[54:55], v[12:13]
	v_cvt_pk_bf16_f32 v218, v10, v11
	v_cvt_pk_bf16_f32 v219, v12, v13
	s_nop 1
	v_permlane32_swap_b32_e32 v216, v218
	v_permlane32_swap_b32_e32 v217, v219
	global_store_dwordx4 v[4:5], v[216:219], off
	v_pk_mul_f32 v[10:11], v[62:63], v[2:3] op_sel_hi:[1,0]
	v_pk_mul_f32 v[12:13], v[50:51], v[2:3] op_sel_hi:[1,0]
	v_pk_mul_f32 v[10:11], v[68:69], v[10:11]
	v_pk_mul_f32 v[12:13], v[108:109], v[12:13]
	v_cvt_pk_bf16_f32 v220, v10, v11
	v_cvt_pk_bf16_f32 v221, v12, v13
	v_pk_mul_f32 v[10:11], v[32:33], v[2:3] op_sel_hi:[1,0]
	v_pk_mul_f32 v[12:13], v[66:67], v[2:3] op_sel_hi:[1,0]
	v_pk_mul_f32 v[10:11], v[96:97], v[10:11]
	v_pk_mul_f32 v[12:13], v[110:111], v[12:13]
	v_cvt_pk_bf16_f32 v222, v10, v11
	v_cvt_pk_bf16_f32 v223, v12, v13
	s_nop 1
	v_permlane32_swap_b32_e32 v220, v222
	v_permlane32_swap_b32_e32 v221, v223
	global_store_dwordx4 v[4:5], v[220:223], off offset:32
	v_pk_mul_f32 v[10:11], v[94:95], v[2:3] op_sel_hi:[1,0]
	v_pk_mul_f32 v[12:13], v[56:57], v[2:3] op_sel_hi:[1,0]
	v_pk_mul_f32 v[10:11], v[126:127], v[10:11]
	v_pk_mul_f32 v[12:13], v[130:131], v[12:13]
	v_cvt_pk_bf16_f32 v224, v10, v11
	v_cvt_pk_bf16_f32 v225, v12, v13
	v_pk_mul_f32 v[10:11], v[136:137], v[2:3] op_sel_hi:[1,0]
	v_pk_mul_f32 v[12:13], v[38:39], v[2:3] op_sel_hi:[1,0]
; DI unsigned pk2(float a, float b) { f32x2 v = {a, b}; return __builtin_bit_cast(unsigned, __builtin_convertvector(v, bfv2)); }
; DI float bflo(unsigned u) { return __uint_as_float(u << 16); }
; DI float bfhi(unsigned u) { return __uint_as_float(u & 0xffff0000u); }
; DI float siluf_(float z) { return z * __builtin_amdgcn_rcpf(1.f + __expf(-z)); }
; DI void attn_item(const Params& p, unsigned char* lds, int b, int hd, int qb, float lam) {
;     ...
; #pragma unroll
;         for (int d = 0; d < 4; ++d)
; #pragma unroll
;             for (int g = 0; g < 4; ++g) {
;                 bf16_t* zp = az + grow * 1024 + hd * 128 + d * 32 + 8 * g + 4 * h;
;                 const u32x2 z2 = zz[d][g];
;                 u32x2 o;
;                 o.x = pk2(O[d][4 * g] * rstd * siluf_(bflo(z2.x)), O[d][4 * g + 1] * rstd * siluf_(bfhi(z2.x)));
;                 o.y = pk2(O[d][4 * g + 2] * rstd * siluf_(bflo(z2.y)), O[d][4 * g + 3] * rstd * siluf_(bfhi(z2.y)));
;                 *(u32x2*)zp = o;
;                 if (g == 3) __builtin_amdgcn_sched_barrier(0);
;             }
	v_pk_mul_f32 v[10:11], v[46:47], v[10:11]
	v_pk_mul_f32 v[12:13], v[92:93], v[12:13]
	v_cvt_pk_bf16_f32 v226, v10, v11
	v_cvt_pk_bf16_f32 v227, v12, v13
	s_nop 1
	v_permlane32_swap_b32_e32 v224, v226
	v_permlane32_swap_b32_e32 v225, v227
	global_store_dwordx4 v[4:5], v[224:227], off offset:64
	v_pk_mul_f32 v[10:11], v[90:91], v[2:3] op_sel_hi:[1,0]
	v_pk_mul_f32 v[12:13], v[34:35], v[2:3] op_sel_hi:[1,0]
	v_pk_mul_f32 v[10:11], v[152:153], v[10:11]
	v_pk_mul_f32 v[12:13], v[154:155], v[12:13]
	v_cvt_pk_bf16_f32 v228, v10, v11
	v_cvt_pk_bf16_f32 v229, v12, v13
	v_pk_mul_f32 v[10:11], v[40:41], v[2:3] op_sel_hi:[1,0]
	v_pk_mul_f32 v[12:13], v[144:145], v[2:3] op_sel_hi:[1,0]
	v_pk_mul_f32 v[10:11], v[88:89], v[10:11]
	v_pk_mul_f32 v[12:13], v[146:147], v[12:13]
	v_cvt_pk_bf16_f32 v230, v10, v11
	v_cvt_pk_bf16_f32 v231, v12, v13
	s_nop 1
	v_permlane32_swap_b32_e32 v228, v230
	v_permlane32_swap_b32_e32 v229, v231
	global_store_dwordx4 v[4:5], v[228:231], off offset:96
	v_pk_mul_f32 v[10:11], v[86:87], v[2:3] op_sel_hi:[1,0]
	v_pk_mul_f32 v[12:13], v[36:37], v[2:3] op_sel_hi:[1,0]
	v_pk_mul_f32 v[10:11], v[148:149], v[10:11]
	v_pk_mul_f32 v[12:13], v[128:129], v[12:13]
	v_cvt_pk_bf16_f32 v232, v10, v11
	v_cvt_pk_bf16_f32 v233, v12, v13
	v_pk_mul_f32 v[10:11], v[138:139], v[2:3] op_sel_hi:[1,0]
	v_pk_mul_f32 v[12:13], v[22:23], v[2:3] op_sel_hi:[1,0]
	v_pk_mul_f32 v[10:11], v[30:31], v[10:11]
	v_pk_mul_f32 v[12:13], v[84:85], v[12:13]
	v_cvt_pk_bf16_f32 v234, v10, v11
	v_cvt_pk_bf16_f32 v235, v12, v13
	s_nop 1
	v_permlane32_swap_b32_e32 v232, v234
	v_permlane32_swap_b32_e32 v233, v235
	global_store_dwordx4 v[4:5], v[232:235], off offset:128
	v_pk_mul_f32 v[10:11], v[80:81], v[2:3] op_sel_hi:[1,0]
	v_pk_mul_f32 v[12:13], v[18:19], v[2:3] op_sel_hi:[1,0]
	v_pk_mul_f32 v[10:11], v[120:121], v[10:11]
	v_pk_mul_f32 v[12:13], v[122:123], v[12:13]
	v_cvt_pk_bf16_f32 v240, v10, v11
	v_cvt_pk_bf16_f32 v241, v12, v13
	v_pk_mul_f32 v[10:11], v[24:25], v[2:3] op_sel_hi:[1,0]
	v_pk_mul_f32 v[12:13], v[112:113], v[2:3] op_sel_hi:[1,0]
	v_pk_mul_f32 v[10:11], v[78:79], v[10:11]
	v_pk_mul_f32 v[12:13], v[114:115], v[12:13]
	v_cvt_pk_bf16_f32 v242, v10, v11
	v_cvt_pk_bf16_f32 v243, v12, v13
	s_nop 1
	v_permlane32_swap_b32_e32 v240, v242
	v_permlane32_swap_b32_e32 v241, v243
	global_store_dwordx4 v[4:5], v[240:243], off offset:160
	v_pk_mul_f32 v[10:11], v[76:77], v[2:3] op_sel_hi:[1,0]
	v_pk_mul_f32 v[12:13], v[20:21], v[2:3] op_sel_hi:[1,0]
	v_pk_mul_f32 v[10:11], v[116:117], v[10:11]
	v_pk_mul_f32 v[12:13], v[100:101], v[12:13]
	v_cvt_pk_bf16_f32 v244, v10, v11
	v_cvt_pk_bf16_f32 v245, v12, v13
	v_pk_mul_f32 v[10:11], v[102:103], v[2:3] op_sel_hi:[1,0]
	v_pk_mul_f32 v[8:9], v[8:9], v[2:3] op_sel_hi:[1,0]
	v_pk_mul_f32 v[10:11], v[104:105], v[10:11]
	v_pk_mul_f32 v[8:9], v[60:61], v[8:9]
	v_cvt_pk_bf16_f32 v246, v10, v11
	v_cvt_pk_bf16_f32 v247, v8, v9
	s_nop 1
	v_permlane32_swap_b32_e32 v244, v246
	v_permlane32_swap_b32_e32 v245, v247
	global_store_dwordx4 v[4:5], v[244:247], off offset:192
	s_waitcnt vmcnt(7)
	v_lshlrev_b32_e32 v10, 16, v70
	v_and_b32_e32 v11, 0xffff0000, v70
	v_mul_f32_e32 v1, 0xbfb8aa3b, v10
	v_exp_f32_e32 v1, v1
	v_mul_f32_e32 v7, 0xbfb8aa3b, v11
	v_exp_f32_e32 v7, v7
	v_pk_mul_f32 v[12:13], v[14:15], v[2:3] op_sel_hi:[1,0]
	v_add_f32_e32 v1, 1.0, v1
	v_rcp_f32_e32 v14, v1
	v_add_f32_e32 v1, 1.0, v7
	v_rcp_f32_e32 v15, v1
	v_pk_mul_f32 v[8:9], v[48:49], v[2:3] op_sel_hi:[1,0]
	v_pk_mul_f32 v[12:13], v[28:29], v[12:13]
	v_pk_mul_f32 v[8:9], v[58:59], v[8:9]
	v_mov_b32_e32 v7, v3
	v_cvt_pk_bf16_f32 v248, v8, v9
	v_cvt_pk_bf16_f32 v249, v12, v13
	v_pk_mul_f32 v[8:9], v[14:15], v[10:11]
	v_lshlrev_b32_e32 v10, 16, v71
	v_and_b32_e32 v11, 0xffff0000, v71
	v_mul_f32_e32 v1, 0xbfb8aa3b, v10
	v_exp_f32_e32 v1, v1
	v_mul_f32_e32 v3, 0xbfb8aa3b, v11
	v_exp_f32_e32 v3, v3
	v_add_f32_e32 v1, 1.0, v1
	v_rcp_f32_e32 v12, v1
	v_add_f32_e32 v1, 1.0, v3
	v_rcp_f32_e32 v13, v1
	v_pk_mul_f32 v[6:7], v[6:7], v[2:3] op_sel_hi:[1,0]
	v_pk_mul_f32 v[2:3], v[26:27], v[2:3] op_sel_hi:[1,0]
	v_pk_mul_f32 v[6:7], v[8:9], v[6:7]
	v_pk_mul_f32 v[8:9], v[12:13], v[10:11]
	v_cvt_pk_bf16_f32 v250, v6, v7
	v_pk_mul_f32 v[2:3], v[8:9], v[2:3]
	s_nop 0
	v_cvt_pk_bf16_f32 v251, v2, v3
	s_nop 1
	v_permlane32_swap_b32_e32 v248, v250
	v_permlane32_swap_b32_e32 v249, v251
	global_store_dwordx4 v[4:5], v[248:251], off offset:224
